# first K-loop iteration of every GEMM unit peeled with srcC=0 first-touch MFMAs; the 128 accumulator-zeroing moves per unit removed; on top of v23
# speedup vs baseline: 1.0530x; 1.0530x over previous
.LBB0_223:
	s_ashr_i32 s43, s42, 31
	s_lshl_b64 s[44:45], s[42:43], 21
	s_add_u32 s44, s12, s44
	s_addc_u32 s45, s13, s45
	s_and_b64 s[48:49], s[2:3], exec
	s_cselect_b32 s43, s45, s51
	s_cselect_b32 s85, s44, s50
	s_ashr_i32 s41, s40, 31
	s_lshl_b64 s[48:49], s[40:41], 21
	s_add_u32 s48, s15, s48
	s_addc_u32 s49, s30, s49
	s_and_b64 s[54:55], s[2:3], exec
	s_cselect_b32 s41, s49, s53
	s_cselect_b32 s86, s48, s52
	s_add_u32 s50, s50, 0x100080
	s_addc_u32 s51, s51, 0
	s_add_u32 s87, s52, 0x100
	s_addc_u32 s88, s53, 0
	s_mov_b32 s89, -2
.Lpeela:
	ds_read_b128 v[130:133], v208
	ds_read_b128 v[134:137], v208 offset:1024
	ds_read_b128 v[138:141], v208 offset:2048
	ds_read_b128 v[142:145], v208 offset:3072
	ds_read_b128 v[146:149], v209
	ds_read_b128 v[150:153], v209 offset:1024
	ds_read_b128 v[154:157], v209 offset:2048
	ds_read_b128 v[158:161], v209 offset:3072
	s_add_u32 s52, s50, 0xfff00080
	s_addc_u32 s53, s51, -1
	s_cmp_eq_u32 s89, 60
	s_cselect_b32 s55, s43, s53
	s_cselect_b32 s54, s85, s52
	s_cselect_b32 s53, s41, s88
	s_cselect_b32 s52, s86, s87
	v_lshl_add_u64 v[204:205], s[50:51], 0, v[192:193]
	s_add_i32 m0, s56, 0xc000
	ds_read_b128 v[162:165], v210
	ds_read_b128 v[166:169], v210 offset:1024
	ds_read_b128 v[170:173], v210 offset:2048
	ds_read_b128 v[174:177], v210 offset:3072
	ds_read_b128 v[200:203], v210 offset:4096
	ds_read_b128 v[212:215], v210 offset:5120
	ds_read_b128 v[216:219], v210 offset:6144
	ds_read_b128 v[224:227], v210 offset:7168
	global_load_lds_dwordx4 v[204:205], off
	v_lshl_add_u64 v[204:205], s[50:51], 0, v[194:195]
	s_add_i32 m0, s56, 0xe000
	s_nop 0
	global_load_lds_dwordx4 v[204:205], off
	s_waitcnt vmcnt(8)
	s_waitcnt lgkmcnt(0)
	s_setprio 1
	s_barrier
	v_mfma_f32_16x16x32_bf16 v[126:129], v[130:133], v[162:165], 0
	v_mfma_f32_16x16x32_bf16 v[122:125], v[138:141], v[162:165], 0
	v_mfma_f32_16x16x32_bf16 v[110:113], v[130:133], v[170:173], 0
	v_mfma_f32_16x16x32_bf16 v[106:109], v[138:141], v[170:173], 0
	v_mfma_f32_16x16x32_bf16 v[94:97], v[130:133], v[200:203], 0
	v_mfma_f32_16x16x32_bf16 v[90:93], v[138:141], v[200:203], 0
	v_mfma_f32_16x16x32_bf16 v[78:81], v[130:133], v[216:219], 0
	v_mfma_f32_16x16x32_bf16 v[74:77], v[138:141], v[216:219], 0
	v_mfma_f32_16x16x32_bf16 v[126:129], v[134:137], v[166:169], v[126:129]
	v_mfma_f32_16x16x32_bf16 v[122:125], v[142:145], v[166:169], v[122:125]
	v_mfma_f32_16x16x32_bf16 v[110:113], v[134:137], v[174:177], v[110:113]
	v_mfma_f32_16x16x32_bf16 v[106:109], v[142:145], v[174:177], v[106:109]
	v_mfma_f32_16x16x32_bf16 v[94:97], v[134:137], v[212:215], v[94:97]
	v_mfma_f32_16x16x32_bf16 v[90:93], v[142:145], v[212:215], v[90:93]
	v_mfma_f32_16x16x32_bf16 v[78:81], v[134:137], v[224:227], v[78:81]
	v_mfma_f32_16x16x32_bf16 v[74:77], v[142:145], v[224:227], v[74:77]
	v_mfma_f32_16x16x32_bf16 v[118:121], v[146:149], v[162:165], 0
	v_mfma_f32_16x16x32_bf16 v[114:117], v[154:157], v[162:165], 0
	v_mfma_f32_16x16x32_bf16 v[102:105], v[146:149], v[170:173], 0
	v_mfma_f32_16x16x32_bf16 v[98:101], v[154:157], v[170:173], 0
	v_mfma_f32_16x16x32_bf16 v[86:89], v[146:149], v[200:203], 0
	v_mfma_f32_16x16x32_bf16 v[82:85], v[154:157], v[200:203], 0
	v_mfma_f32_16x16x32_bf16 v[70:73], v[146:149], v[216:219], 0
	v_mfma_f32_16x16x32_bf16 v[66:69], v[154:157], v[216:219], 0
	v_mfma_f32_16x16x32_bf16 v[118:121], v[150:153], v[166:169], v[118:121]
	v_mfma_f32_16x16x32_bf16 v[114:117], v[158:161], v[166:169], v[114:117]
	v_mfma_f32_16x16x32_bf16 v[102:105], v[150:153], v[174:177], v[102:105]
	v_mfma_f32_16x16x32_bf16 v[98:101], v[158:161], v[174:177], v[98:101]
	v_mfma_f32_16x16x32_bf16 v[86:89], v[150:153], v[212:215], v[86:89]
	v_mfma_f32_16x16x32_bf16 v[82:85], v[158:161], v[212:215], v[82:85]
	v_mfma_f32_16x16x32_bf16 v[70:73], v[150:153], v[224:227], v[70:73]
	v_mfma_f32_16x16x32_bf16 v[66:69], v[158:161], v[224:227], v[66:69]
	s_barrier
	s_setprio 0
	s_add_i32 s90, s65, s31
	v_lshl_add_u64 v[204:205], s[52:53], 0, v[182:183]
	s_mov_b32 m0, s90
	ds_read_b128 v[162:165], v210 offset:16384
	ds_read_b128 v[166:169], v210 offset:17408
	ds_read_b128 v[170:173], v210 offset:18432
	ds_read_b128 v[174:177], v210 offset:19456
	ds_read_b128 v[200:203], v210 offset:20480
	ds_read_b128 v[212:215], v210 offset:21504
	ds_read_b128 v[216:219], v210 offset:22528
	ds_read_b128 v[224:227], v210 offset:23552
	global_load_lds_dwordx4 v[204:205], off
	s_add_i32 m0, s90, 0x2000
	s_add_u32 s90, s52, 0x100000
	v_lshl_add_u64 v[220:221], s[52:53], 0, v[178:179]
	s_addc_u32 s91, s53, 0
	s_add_i32 s92, s66, s31
	global_load_lds_dwordx4 v[220:221], off
	v_lshl_add_u64 v[228:229], s[90:91], 0, v[182:183]
	s_mov_b32 m0, s92
	v_lshl_add_u64 v[230:231], s[54:55], 0, v[180:181]
	global_load_lds_dwordx4 v[228:229], off
	v_lshl_add_u64 v[228:229], s[90:91], 0, v[178:179]
	s_add_i32 m0, s92, 0x2000
	s_nop 0
	global_load_lds_dwordx4 v[228:229], off
	v_lshl_add_u64 v[228:229], s[54:55], 0, v[184:185]
	s_mov_b32 m0, s56
	s_nop 0
	global_load_lds_dwordx4 v[228:229], off
	s_mov_b32 m0, s57
	s_nop 0
	global_load_lds_dwordx4 v[230:231], off
	s_waitcnt vmcnt(8)
	s_waitcnt lgkmcnt(0)
	s_setprio 1
	s_barrier
	v_mfma_f32_16x16x32_bf16 v[62:65], v[130:133], v[162:165], 0
	v_mfma_f32_16x16x32_bf16 v[58:61], v[138:141], v[162:165], 0
	v_mfma_f32_16x16x32_bf16 v[50:53], v[130:133], v[170:173], 0
	v_mfma_f32_16x16x32_bf16 v[42:45], v[138:141], v[170:173], 0
	v_mfma_f32_16x16x32_bf16 v[34:37], v[130:133], v[200:203], 0
	v_mfma_f32_16x16x32_bf16 v[26:29], v[138:141], v[200:203], 0
	v_mfma_f32_16x16x32_bf16 v[18:21], v[130:133], v[216:219], 0
	v_mfma_f32_16x16x32_bf16 v[10:13], v[138:141], v[216:219], 0
	v_mfma_f32_16x16x32_bf16 v[62:65], v[134:137], v[166:169], v[62:65]
	v_mfma_f32_16x16x32_bf16 v[58:61], v[142:145], v[166:169], v[58:61]
	v_mfma_f32_16x16x32_bf16 v[50:53], v[134:137], v[174:177], v[50:53]
	v_mfma_f32_16x16x32_bf16 v[42:45], v[142:145], v[174:177], v[42:45]
	v_mfma_f32_16x16x32_bf16 v[34:37], v[134:137], v[212:215], v[34:37]
	v_mfma_f32_16x16x32_bf16 v[26:29], v[142:145], v[212:215], v[26:29]
	v_mfma_f32_16x16x32_bf16 v[18:21], v[134:137], v[224:227], v[18:21]
	v_mfma_f32_16x16x32_bf16 v[10:13], v[142:145], v[224:227], v[10:13]
	v_mfma_f32_16x16x32_bf16 v[54:57], v[146:149], v[162:165], 0
	v_mfma_f32_16x16x32_bf16 v[46:49], v[154:157], v[162:165], 0
	v_mfma_f32_16x16x32_bf16 v[38:41], v[146:149], v[170:173], 0
	v_mfma_f32_16x16x32_bf16 v[30:33], v[154:157], v[170:173], 0
	v_mfma_f32_16x16x32_bf16 v[22:25], v[146:149], v[200:203], 0
	v_mfma_f32_16x16x32_bf16 v[14:17], v[154:157], v[200:203], 0
	v_mfma_f32_16x16x32_bf16 v[6:9], v[146:149], v[216:219], 0
	v_mfma_f32_16x16x32_bf16 v[2:5], v[154:157], v[216:219], 0
	v_mfma_f32_16x16x32_bf16 v[54:57], v[150:153], v[166:169], v[54:57]
	v_mfma_f32_16x16x32_bf16 v[46:49], v[158:161], v[166:169], v[46:49]
	v_mfma_f32_16x16x32_bf16 v[38:41], v[150:153], v[174:177], v[38:41]
	v_mfma_f32_16x16x32_bf16 v[30:33], v[158:161], v[174:177], v[30:33]
	v_mfma_f32_16x16x32_bf16 v[22:25], v[150:153], v[212:215], v[22:25]
	v_mfma_f32_16x16x32_bf16 v[14:17], v[158:161], v[212:215], v[14:17]
	v_mfma_f32_16x16x32_bf16 v[6:9], v[150:153], v[224:227], v[6:9]
	v_mfma_f32_16x16x32_bf16 v[2:5], v[158:161], v[224:227], v[2:5]
	s_barrier
	s_setprio 0
	s_add_i32 s90, 0, 0x18000
	s_add_i32 s91, 0, 0x1c000
	v_add_u32_e32 v142, s90, v189
	v_add_u32_e32 v158, s91, v189
	ds_read_b128 v[130:133], v142
	ds_read_b128 v[134:137], v142 offset:1024
	ds_read_b128 v[138:141], v142 offset:2048
	ds_read_b128 v[142:145], v142 offset:3072
	ds_read_b128 v[146:149], v158
	ds_read_b128 v[150:153], v158 offset:1024
	ds_read_b128 v[154:157], v158 offset:2048
	ds_read_b128 v[158:161], v158 offset:3072
	s_add_u32 s54, s54, 0x100000
	s_addc_u32 s55, s55, 0
	s_mov_b32 m0, s58
	v_lshl_add_u64 v[232:233], s[54:55], 0, v[184:185]
	ds_read_b128 v[162:165], v210 offset:32768
	ds_read_b128 v[166:169], v210 offset:33792
	ds_read_b128 v[170:173], v210 offset:34816
	ds_read_b128 v[174:177], v210 offset:35840
	ds_read_b128 v[200:203], v210 offset:36864
	ds_read_b128 v[212:215], v210 offset:37888
	ds_read_b128 v[216:219], v210 offset:38912
	ds_read_b128 v[224:227], v210 offset:39936
	global_load_lds_dwordx4 v[232:233], off
	v_lshl_add_u64 v[232:233], s[54:55], 0, v[180:181]
	s_mov_b32 m0, s59
	s_nop 0
	global_load_lds_dwordx4 v[232:233], off
	s_waitcnt vmcnt(8)
	s_waitcnt lgkmcnt(0)
	s_setprio 1
	s_barrier
	v_mfma_f32_16x16x32_bf16 v[126:129], v[130:133], v[162:165], v[126:129]
	v_mfma_f32_16x16x32_bf16 v[122:125], v[138:141], v[162:165], v[122:125]
	v_mfma_f32_16x16x32_bf16 v[110:113], v[130:133], v[170:173], v[110:113]
	v_mfma_f32_16x16x32_bf16 v[106:109], v[138:141], v[170:173], v[106:109]
	v_mfma_f32_16x16x32_bf16 v[94:97], v[130:133], v[200:203], v[94:97]
	v_mfma_f32_16x16x32_bf16 v[90:93], v[138:141], v[200:203], v[90:93]
	v_mfma_f32_16x16x32_bf16 v[78:81], v[130:133], v[216:219], v[78:81]
	v_mfma_f32_16x16x32_bf16 v[74:77], v[138:141], v[216:219], v[74:77]
	v_mfma_f32_16x16x32_bf16 v[126:129], v[134:137], v[166:169], v[126:129]
	v_mfma_f32_16x16x32_bf16 v[122:125], v[142:145], v[166:169], v[122:125]
	v_mfma_f32_16x16x32_bf16 v[110:113], v[134:137], v[174:177], v[110:113]
	v_mfma_f32_16x16x32_bf16 v[106:109], v[142:145], v[174:177], v[106:109]
	v_mfma_f32_16x16x32_bf16 v[94:97], v[134:137], v[212:215], v[94:97]
	v_mfma_f32_16x16x32_bf16 v[90:93], v[142:145], v[212:215], v[90:93]
	v_mfma_f32_16x16x32_bf16 v[78:81], v[134:137], v[224:227], v[78:81]
	v_mfma_f32_16x16x32_bf16 v[74:77], v[142:145], v[224:227], v[74:77]
	v_mfma_f32_16x16x32_bf16 v[118:121], v[146:149], v[162:165], v[118:121]
	v_mfma_f32_16x16x32_bf16 v[114:117], v[154:157], v[162:165], v[114:117]
	v_mfma_f32_16x16x32_bf16 v[102:105], v[146:149], v[170:173], v[102:105]
	v_mfma_f32_16x16x32_bf16 v[98:101], v[154:157], v[170:173], v[98:101]
	v_mfma_f32_16x16x32_bf16 v[86:89], v[146:149], v[200:203], v[86:89]
	v_mfma_f32_16x16x32_bf16 v[82:85], v[154:157], v[200:203], v[82:85]
	v_mfma_f32_16x16x32_bf16 v[70:73], v[146:149], v[216:219], v[70:73]
	v_mfma_f32_16x16x32_bf16 v[66:69], v[154:157], v[216:219], v[66:69]
	v_mfma_f32_16x16x32_bf16 v[118:121], v[150:153], v[166:169], v[118:121]
	v_mfma_f32_16x16x32_bf16 v[114:117], v[158:161], v[166:169], v[114:117]
	v_mfma_f32_16x16x32_bf16 v[102:105], v[150:153], v[174:177], v[102:105]
	v_mfma_f32_16x16x32_bf16 v[98:101], v[158:161], v[174:177], v[98:101]
	v_mfma_f32_16x16x32_bf16 v[86:89], v[150:153], v[212:215], v[86:89]
	v_mfma_f32_16x16x32_bf16 v[82:85], v[158:161], v[212:215], v[82:85]
	v_mfma_f32_16x16x32_bf16 v[70:73], v[150:153], v[224:227], v[70:73]
	v_mfma_f32_16x16x32_bf16 v[66:69], v[158:161], v[224:227], v[66:69]
	s_barrier
	s_setprio 0
	s_add_i32 s54, s90, s31
	v_lshl_add_u64 v[204:205], v[204:205], 0, s[8:9]
	s_mov_b32 m0, s54
	ds_read_b128 v[162:165], v210 offset:49152
	ds_read_b128 v[166:169], v210 offset:50176
	ds_read_b128 v[170:173], v210 offset:51200
	ds_read_b128 v[174:177], v210 offset:52224
	ds_read_b128 v[200:203], v210 offset:53248
	ds_read_b128 v[212:215], v210 offset:54272
	ds_read_b128 v[216:219], v210 offset:55296
	ds_read_b128 v[224:227], v210 offset:56320
	global_load_lds_dwordx4 v[204:205], off
	s_add_i32 m0, s54, 0x2000
	s_add_u32 s52, s52, 0x100080
	v_lshl_add_u64 v[204:205], v[220:221], 0, s[8:9]
	s_addc_u32 s53, s53, 0
	s_add_i32 s54, s91, s31
	global_load_lds_dwordx4 v[204:205], off
	v_lshl_add_u64 v[204:205], s[52:53], 0, v[182:183]
	s_mov_b32 m0, s54
	s_nop 0
	global_load_lds_dwordx4 v[204:205], off
	v_lshl_add_u64 v[204:205], s[52:53], 0, v[178:179]
	s_add_i32 m0, s54, 0x2000
	s_nop 0
	global_load_lds_dwordx4 v[204:205], off
	v_lshl_add_u64 v[204:205], v[228:229], 0, s[8:9]
	s_mov_b32 m0, s62
	s_nop 0
	global_load_lds_dwordx4 v[204:205], off
	v_lshl_add_u64 v[204:205], v[230:231], 0, s[8:9]
	s_mov_b32 m0, s63
	s_nop 0
	global_load_lds_dwordx4 v[204:205], off
	s_waitcnt vmcnt(8)
	s_waitcnt lgkmcnt(0)
	s_setprio 1
	s_barrier
	v_mfma_f32_16x16x32_bf16 v[62:65], v[130:133], v[162:165], v[62:65]
	v_mfma_f32_16x16x32_bf16 v[58:61], v[138:141], v[162:165], v[58:61]
	v_mfma_f32_16x16x32_bf16 v[50:53], v[130:133], v[170:173], v[50:53]
	v_mfma_f32_16x16x32_bf16 v[42:45], v[138:141], v[170:173], v[42:45]
	v_mfma_f32_16x16x32_bf16 v[34:37], v[130:133], v[200:203], v[34:37]
	v_mfma_f32_16x16x32_bf16 v[26:29], v[138:141], v[200:203], v[26:29]
	v_mfma_f32_16x16x32_bf16 v[18:21], v[130:133], v[216:219], v[18:21]
	v_mfma_f32_16x16x32_bf16 v[10:13], v[138:141], v[216:219], v[10:13]
	v_mfma_f32_16x16x32_bf16 v[62:65], v[134:137], v[166:169], v[62:65]
	v_mfma_f32_16x16x32_bf16 v[58:61], v[142:145], v[166:169], v[58:61]
	v_mfma_f32_16x16x32_bf16 v[50:53], v[134:137], v[174:177], v[50:53]
	v_mfma_f32_16x16x32_bf16 v[42:45], v[142:145], v[174:177], v[42:45]
	v_mfma_f32_16x16x32_bf16 v[34:37], v[134:137], v[212:215], v[34:37]
	v_mfma_f32_16x16x32_bf16 v[26:29], v[142:145], v[212:215], v[26:29]
	v_mfma_f32_16x16x32_bf16 v[18:21], v[134:137], v[224:227], v[18:21]
	v_mfma_f32_16x16x32_bf16 v[10:13], v[142:145], v[224:227], v[10:13]
	v_mfma_f32_16x16x32_bf16 v[54:57], v[146:149], v[162:165], v[54:57]
	v_mfma_f32_16x16x32_bf16 v[46:49], v[154:157], v[162:165], v[46:49]
	v_mfma_f32_16x16x32_bf16 v[38:41], v[146:149], v[170:173], v[38:41]
	v_mfma_f32_16x16x32_bf16 v[30:33], v[154:157], v[170:173], v[30:33]
	v_mfma_f32_16x16x32_bf16 v[22:25], v[146:149], v[200:203], v[22:25]
	v_mfma_f32_16x16x32_bf16 v[14:17], v[154:157], v[200:203], v[14:17]
	v_mfma_f32_16x16x32_bf16 v[6:9], v[146:149], v[216:219], v[6:9]
	v_mfma_f32_16x16x32_bf16 v[2:5], v[154:157], v[216:219], v[2:5]
	v_mfma_f32_16x16x32_bf16 v[54:57], v[150:153], v[166:169], v[54:57]
	v_mfma_f32_16x16x32_bf16 v[46:49], v[158:161], v[166:169], v[46:49]
	v_mfma_f32_16x16x32_bf16 v[38:41], v[150:153], v[174:177], v[38:41]
	v_mfma_f32_16x16x32_bf16 v[30:33], v[158:161], v[174:177], v[30:33]
	v_mfma_f32_16x16x32_bf16 v[22:25], v[150:153], v[212:215], v[22:25]
	v_mfma_f32_16x16x32_bf16 v[14:17], v[158:161], v[212:215], v[14:17]
	v_mfma_f32_16x16x32_bf16 v[6:9], v[150:153], v[224:227], v[6:9]
	v_mfma_f32_16x16x32_bf16 v[2:5], v[158:161], v[224:227], v[2:5]
	s_barrier
	s_setprio 0
	s_add_i32 s89, s89, 2
	s_add_u32 s50, s50, 0x100
	s_addc_u32 s51, s51, 0
	s_add_u32 s87, s87, 0x100
	s_addc_u32 s88, s88, 0

.LBB0_671:
	s_and_b64 s[18:19], s[56:57], exec
	s_cselect_b32 s18, s30, s30
	s_cselect_b32 s20, s53, s1
	s_cselect_b32 s21, s52, s0
	s_ashr_i32 s19, s18, 31
	s_lshl_b64 s[18:19], s[18:19], 21
	s_mov_b64 s[16:17], s[38:39]
	s_add_u32 s38, s12, s18
	s_addc_u32 s39, s13, s19
	s_and_b64 s[18:19], s[56:57], exec
	s_cselect_b32 s22, s39, s17
	s_cselect_b32 s23, s38, s16
	s_add_u32 s0, s0, 0x100080
	s_addc_u32 s1, s1, 0
	s_add_u32 s24, s16, 0x100
	s_addc_u32 s25, s17, 0
	s_mov_b32 s26, -2
.Lpeelb:
	v_add_u32_e32 v142, s51, v220
	v_add_u32_e32 v158, s81, v220
	ds_read_b128 v[130:133], v142
	ds_read_b128 v[134:137], v142 offset:1024
	ds_read_b128 v[138:141], v142 offset:2048
	ds_read_b128 v[142:145], v142 offset:3072
	ds_read_b128 v[146:149], v158
	ds_read_b128 v[150:153], v158 offset:1024
	ds_read_b128 v[154:157], v158 offset:2048
	ds_read_b128 v[158:161], v158 offset:3072
	s_add_u32 s16, s0, 0xfff00080
	s_addc_u32 s17, s1, -1
	s_cmp_eq_u32 s26, 60
	s_cselect_b32 s19, s20, s17
	s_cselect_b32 s18, s21, s16
	s_cselect_b32 s17, s22, s25
	s_cselect_b32 s16, s23, s24
	v_lshl_add_u64 v[218:219], s[0:1], 0, v[194:195]
	s_add_i32 m0, s31, 0xc000
	ds_read_b128 v[162:165], v233
	ds_read_b128 v[166:169], v233 offset:1024
	ds_read_b128 v[170:173], v233 offset:2048
	ds_read_b128 v[174:177], v233 offset:3072
	ds_read_b128 v[202:205], v233 offset:4096
	ds_read_b128 v[206:209], v233 offset:5120
	ds_read_b128 v[210:213], v233 offset:6144
	ds_read_b128 v[214:217], v233 offset:7168
	global_load_lds_dwordx4 v[218:219], off
	v_lshl_add_u64 v[218:219], s[0:1], 0, v[196:197]
	s_add_i32 m0, s31, 0xe000
	s_nop 0
	global_load_lds_dwordx4 v[218:219], off
	s_waitcnt vmcnt(8)
	s_waitcnt lgkmcnt(0)
	s_setprio 1
	s_barrier
	v_mfma_f32_16x16x32_bf16 v[90:93], v[130:133], v[162:165], 0
	v_mfma_f32_16x16x32_bf16 v[58:61], v[138:141], v[162:165], 0
	v_mfma_f32_16x16x32_bf16 v[98:101], v[130:133], v[170:173], 0
	v_mfma_f32_16x16x32_bf16 v[66:69], v[138:141], v[170:173], 0
	v_mfma_f32_16x16x32_bf16 v[102:105], v[130:133], v[202:205], 0
	v_mfma_f32_16x16x32_bf16 v[70:73], v[138:141], v[202:205], 0
	v_mfma_f32_16x16x32_bf16 v[110:113], v[130:133], v[210:213], 0
	v_mfma_f32_16x16x32_bf16 v[78:81], v[138:141], v[210:213], 0
	v_mfma_f32_16x16x32_bf16 v[90:93], v[134:137], v[166:169], v[90:93]
	v_mfma_f32_16x16x32_bf16 v[58:61], v[142:145], v[166:169], v[58:61]
	v_mfma_f32_16x16x32_bf16 v[98:101], v[134:137], v[174:177], v[98:101]
	v_mfma_f32_16x16x32_bf16 v[66:69], v[142:145], v[174:177], v[66:69]
	v_mfma_f32_16x16x32_bf16 v[102:105], v[134:137], v[206:209], v[102:105]
	v_mfma_f32_16x16x32_bf16 v[70:73], v[142:145], v[206:209], v[70:73]
	v_mfma_f32_16x16x32_bf16 v[110:113], v[134:137], v[214:217], v[110:113]
	v_mfma_f32_16x16x32_bf16 v[78:81], v[142:145], v[214:217], v[78:81]
	v_mfma_f32_16x16x32_bf16 v[26:29], v[146:149], v[162:165], 0
	v_mfma_f32_16x16x32_bf16 v[2:5], v[154:157], v[162:165], 0
	v_mfma_f32_16x16x32_bf16 v[34:37], v[146:149], v[170:173], 0
	v_mfma_f32_16x16x32_bf16 v[6:9], v[154:157], v[170:173], 0
	v_mfma_f32_16x16x32_bf16 v[38:41], v[146:149], v[202:205], 0
	v_mfma_f32_16x16x32_bf16 v[10:13], v[154:157], v[202:205], 0
	v_mfma_f32_16x16x32_bf16 v[46:49], v[146:149], v[210:213], 0
	v_mfma_f32_16x16x32_bf16 v[14:17], v[154:157], v[210:213], 0
	v_mfma_f32_16x16x32_bf16 v[26:29], v[150:153], v[166:169], v[26:29]
	v_mfma_f32_16x16x32_bf16 v[2:5], v[158:161], v[166:169], v[2:5]
	v_mfma_f32_16x16x32_bf16 v[34:37], v[150:153], v[174:177], v[34:37]
	v_mfma_f32_16x16x32_bf16 v[6:9], v[158:161], v[174:177], v[6:9]
	v_mfma_f32_16x16x32_bf16 v[38:41], v[150:153], v[206:209], v[38:41]
	v_mfma_f32_16x16x32_bf16 v[10:13], v[158:161], v[206:209], v[10:13]
	v_mfma_f32_16x16x32_bf16 v[46:49], v[150:153], v[214:217], v[46:49]
	v_mfma_f32_16x16x32_bf16 v[14:17], v[158:161], v[214:217], v[14:17]
	s_barrier
	s_setprio 0
	s_add_i32 s27, s51, s15
	v_lshl_add_u64 v[218:219], s[16:17], 0, v[178:179]
	s_mov_b32 m0, s27
	ds_read_b128 v[162:165], v233 offset:16384
	ds_read_b128 v[166:169], v233 offset:17408
	ds_read_b128 v[170:173], v233 offset:18432
	ds_read_b128 v[174:177], v233 offset:19456
	ds_read_b128 v[202:205], v233 offset:20480
	ds_read_b128 v[206:209], v233 offset:21504
	ds_read_b128 v[210:213], v233 offset:22528
	ds_read_b128 v[214:217], v233 offset:23552
	global_load_lds_dwordx4 v[218:219], off
	s_add_i32 m0, s27, 0x2000
	s_add_u32 s62, s16, 0x100000
	v_lshl_add_u64 v[242:243], s[16:17], 0, v[180:181]
	s_addc_u32 s63, s17, 0
	s_add_i32 s27, s81, s15
	global_load_lds_dwordx4 v[242:243], off
	v_lshl_add_u64 v[244:245], s[62:63], 0, v[178:179]
	s_mov_b32 m0, s27
	v_lshl_add_u64 v[246:247], s[18:19], 0, v[180:181]
	global_load_lds_dwordx4 v[244:245], off
	v_lshl_add_u64 v[244:245], s[62:63], 0, v[180:181]
	s_add_i32 m0, s27, 0x2000
	s_nop 0
	global_load_lds_dwordx4 v[244:245], off
	v_lshl_add_u64 v[244:245], s[18:19], 0, v[178:179]
	s_mov_b32 m0, s31
	s_nop 0
	global_load_lds_dwordx4 v[244:245], off
	s_mov_b32 m0, s34
	s_nop 0
	global_load_lds_dwordx4 v[246:247], off
	s_waitcnt vmcnt(8)
	s_waitcnt lgkmcnt(0)
	s_setprio 1
	s_barrier
	v_mfma_f32_16x16x32_bf16 v[114:117], v[130:133], v[162:165], 0
	v_mfma_f32_16x16x32_bf16 v[82:85], v[138:141], v[162:165], 0
	v_mfma_f32_16x16x32_bf16 v[118:121], v[130:133], v[170:173], 0
	v_mfma_f32_16x16x32_bf16 v[86:89], v[138:141], v[170:173], 0
	v_mfma_f32_16x16x32_bf16 v[122:125], v[130:133], v[202:205], 0
	v_mfma_f32_16x16x32_bf16 v[94:97], v[138:141], v[202:205], 0
	v_mfma_f32_16x16x32_bf16 v[126:129], v[130:133], v[210:213], 0
	v_mfma_f32_16x16x32_bf16 v[106:109], v[138:141], v[210:213], 0
	v_mfma_f32_16x16x32_bf16 v[114:117], v[134:137], v[166:169], v[114:117]
	v_mfma_f32_16x16x32_bf16 v[82:85], v[142:145], v[166:169], v[82:85]
	v_mfma_f32_16x16x32_bf16 v[118:121], v[134:137], v[174:177], v[118:121]
	v_mfma_f32_16x16x32_bf16 v[86:89], v[142:145], v[174:177], v[86:89]
	v_mfma_f32_16x16x32_bf16 v[122:125], v[134:137], v[206:209], v[122:125]
	v_mfma_f32_16x16x32_bf16 v[94:97], v[142:145], v[206:209], v[94:97]
	v_mfma_f32_16x16x32_bf16 v[126:129], v[134:137], v[214:217], v[126:129]
	v_mfma_f32_16x16x32_bf16 v[106:109], v[142:145], v[214:217], v[106:109]
	v_mfma_f32_16x16x32_bf16 v[50:53], v[146:149], v[162:165], 0
	v_mfma_f32_16x16x32_bf16 v[18:21], v[154:157], v[162:165], 0
	v_mfma_f32_16x16x32_bf16 v[54:57], v[146:149], v[170:173], 0
	v_mfma_f32_16x16x32_bf16 v[22:25], v[154:157], v[170:173], 0
	v_mfma_f32_16x16x32_bf16 v[62:65], v[146:149], v[202:205], 0
	v_mfma_f32_16x16x32_bf16 v[30:33], v[154:157], v[202:205], 0
	v_mfma_f32_16x16x32_bf16 v[74:77], v[146:149], v[210:213], 0
	v_mfma_f32_16x16x32_bf16 v[42:45], v[154:157], v[210:213], 0
	v_mfma_f32_16x16x32_bf16 v[50:53], v[150:153], v[166:169], v[50:53]
	v_mfma_f32_16x16x32_bf16 v[18:21], v[158:161], v[166:169], v[18:21]
	v_mfma_f32_16x16x32_bf16 v[54:57], v[150:153], v[174:177], v[54:57]
	v_mfma_f32_16x16x32_bf16 v[22:25], v[158:161], v[174:177], v[22:25]
	v_mfma_f32_16x16x32_bf16 v[62:65], v[150:153], v[206:209], v[62:65]
	v_mfma_f32_16x16x32_bf16 v[30:33], v[158:161], v[206:209], v[30:33]
	v_mfma_f32_16x16x32_bf16 v[74:77], v[150:153], v[214:217], v[74:77]
	v_mfma_f32_16x16x32_bf16 v[42:45], v[158:161], v[214:217], v[42:45]
	s_barrier
	s_setprio 0
	s_add_i32 s27, 0, 0x18000
	s_add_i32 s59, 0, 0x1c000
	v_add_u32_e32 v142, s27, v220
	v_add_u32_e32 v158, s59, v220
	ds_read_b128 v[130:133], v142
	ds_read_b128 v[134:137], v142 offset:1024
	ds_read_b128 v[138:141], v142 offset:2048
	ds_read_b128 v[142:145], v142 offset:3072
	ds_read_b128 v[146:149], v158
	ds_read_b128 v[150:153], v158 offset:1024
	ds_read_b128 v[154:157], v158 offset:2048
	ds_read_b128 v[158:161], v158 offset:3072
	s_add_u32 s18, s18, 0x100000
	s_addc_u32 s19, s19, 0
	s_mov_b32 m0, s35
	v_lshl_add_u64 v[248:249], s[18:19], 0, v[178:179]
	ds_read_b128 v[162:165], v233 offset:32768
	ds_read_b128 v[166:169], v233 offset:33792
	ds_read_b128 v[170:173], v233 offset:34816
	ds_read_b128 v[174:177], v233 offset:35840
	ds_read_b128 v[202:205], v233 offset:36864
	ds_read_b128 v[206:209], v233 offset:37888
	ds_read_b128 v[210:213], v233 offset:38912
	ds_read_b128 v[214:217], v233 offset:39936
	global_load_lds_dwordx4 v[248:249], off
	v_lshl_add_u64 v[248:249], s[18:19], 0, v[180:181]
	s_mov_b32 m0, s86
	s_nop 0
	global_load_lds_dwordx4 v[248:249], off
	s_waitcnt vmcnt(8)
	s_waitcnt lgkmcnt(0)
	s_setprio 1
	s_barrier
	v_mfma_f32_16x16x32_bf16 v[90:93], v[130:133], v[162:165], v[90:93]
	v_mfma_f32_16x16x32_bf16 v[58:61], v[138:141], v[162:165], v[58:61]
	v_mfma_f32_16x16x32_bf16 v[98:101], v[130:133], v[170:173], v[98:101]
	v_mfma_f32_16x16x32_bf16 v[66:69], v[138:141], v[170:173], v[66:69]
	v_mfma_f32_16x16x32_bf16 v[102:105], v[130:133], v[202:205], v[102:105]
	v_mfma_f32_16x16x32_bf16 v[70:73], v[138:141], v[202:205], v[70:73]
	v_mfma_f32_16x16x32_bf16 v[110:113], v[130:133], v[210:213], v[110:113]
	v_mfma_f32_16x16x32_bf16 v[78:81], v[138:141], v[210:213], v[78:81]
	v_mfma_f32_16x16x32_bf16 v[90:93], v[134:137], v[166:169], v[90:93]
	v_mfma_f32_16x16x32_bf16 v[58:61], v[142:145], v[166:169], v[58:61]
	v_mfma_f32_16x16x32_bf16 v[98:101], v[134:137], v[174:177], v[98:101]
	v_mfma_f32_16x16x32_bf16 v[66:69], v[142:145], v[174:177], v[66:69]
	v_mfma_f32_16x16x32_bf16 v[102:105], v[134:137], v[206:209], v[102:105]
	v_mfma_f32_16x16x32_bf16 v[70:73], v[142:145], v[206:209], v[70:73]
	v_mfma_f32_16x16x32_bf16 v[110:113], v[134:137], v[214:217], v[110:113]
	v_mfma_f32_16x16x32_bf16 v[78:81], v[142:145], v[214:217], v[78:81]
	v_mfma_f32_16x16x32_bf16 v[26:29], v[146:149], v[162:165], v[26:29]
	v_mfma_f32_16x16x32_bf16 v[2:5], v[154:157], v[162:165], v[2:5]
	v_mfma_f32_16x16x32_bf16 v[34:37], v[146:149], v[170:173], v[34:37]
	v_mfma_f32_16x16x32_bf16 v[6:9], v[154:157], v[170:173], v[6:9]
	v_mfma_f32_16x16x32_bf16 v[38:41], v[146:149], v[202:205], v[38:41]
	v_mfma_f32_16x16x32_bf16 v[10:13], v[154:157], v[202:205], v[10:13]
	v_mfma_f32_16x16x32_bf16 v[46:49], v[146:149], v[210:213], v[46:49]
	v_mfma_f32_16x16x32_bf16 v[14:17], v[154:157], v[210:213], v[14:17]
	v_mfma_f32_16x16x32_bf16 v[26:29], v[150:153], v[166:169], v[26:29]
	v_mfma_f32_16x16x32_bf16 v[2:5], v[158:161], v[166:169], v[2:5]
	v_mfma_f32_16x16x32_bf16 v[34:37], v[150:153], v[174:177], v[34:37]
	v_mfma_f32_16x16x32_bf16 v[6:9], v[158:161], v[174:177], v[6:9]
	v_mfma_f32_16x16x32_bf16 v[38:41], v[150:153], v[206:209], v[38:41]
	v_mfma_f32_16x16x32_bf16 v[10:13], v[158:161], v[206:209], v[10:13]
	v_mfma_f32_16x16x32_bf16 v[46:49], v[150:153], v[214:217], v[46:49]
	v_mfma_f32_16x16x32_bf16 v[14:17], v[158:161], v[214:217], v[14:17]
	s_barrier
	s_setprio 0
	s_add_i32 s18, s27, s15
	v_lshl_add_u64 v[218:219], v[218:219], 0, s[44:45]
	s_mov_b32 m0, s18
	ds_read_b128 v[162:165], v233 offset:49152
	ds_read_b128 v[166:169], v233 offset:50176
	ds_read_b128 v[170:173], v233 offset:51200
	ds_read_b128 v[174:177], v233 offset:52224
	ds_read_b128 v[202:205], v233 offset:53248
	ds_read_b128 v[206:209], v233 offset:54272
	ds_read_b128 v[210:213], v233 offset:55296
	ds_read_b128 v[214:217], v233 offset:56320
	global_load_lds_dwordx4 v[218:219], off
	s_add_i32 m0, s18, 0x2000
	s_add_u32 s16, s16, 0x100080
	v_lshl_add_u64 v[218:219], v[242:243], 0, s[44:45]
	s_addc_u32 s17, s17, 0
	s_add_i32 s18, s59, s15
	global_load_lds_dwordx4 v[218:219], off
	v_lshl_add_u64 v[218:219], s[16:17], 0, v[178:179]
	s_mov_b32 m0, s18
	s_nop 0
	global_load_lds_dwordx4 v[218:219], off
	v_lshl_add_u64 v[218:219], s[16:17], 0, v[180:181]
	s_add_i32 m0, s18, 0x2000
	s_nop 0
	global_load_lds_dwordx4 v[218:219], off
	v_lshl_add_u64 v[218:219], v[244:245], 0, s[44:45]
	s_mov_b32 m0, s66
	s_nop 0
	global_load_lds_dwordx4 v[218:219], off
	v_lshl_add_u64 v[218:219], v[246:247], 0, s[44:45]
	s_mov_b32 m0, s67
	s_nop 0
	global_load_lds_dwordx4 v[218:219], off
	s_waitcnt vmcnt(8)
	s_waitcnt lgkmcnt(0)
	s_setprio 1
	s_barrier
	v_mfma_f32_16x16x32_bf16 v[114:117], v[130:133], v[162:165], v[114:117]
	v_mfma_f32_16x16x32_bf16 v[82:85], v[138:141], v[162:165], v[82:85]
	v_mfma_f32_16x16x32_bf16 v[118:121], v[130:133], v[170:173], v[118:121]
	v_mfma_f32_16x16x32_bf16 v[86:89], v[138:141], v[170:173], v[86:89]
	v_mfma_f32_16x16x32_bf16 v[122:125], v[130:133], v[202:205], v[122:125]
	v_mfma_f32_16x16x32_bf16 v[94:97], v[138:141], v[202:205], v[94:97]
	v_mfma_f32_16x16x32_bf16 v[126:129], v[130:133], v[210:213], v[126:129]
	v_mfma_f32_16x16x32_bf16 v[106:109], v[138:141], v[210:213], v[106:109]
	v_mfma_f32_16x16x32_bf16 v[114:117], v[134:137], v[166:169], v[114:117]
	v_mfma_f32_16x16x32_bf16 v[82:85], v[142:145], v[166:169], v[82:85]
	v_mfma_f32_16x16x32_bf16 v[118:121], v[134:137], v[174:177], v[118:121]
	v_mfma_f32_16x16x32_bf16 v[86:89], v[142:145], v[174:177], v[86:89]
	v_mfma_f32_16x16x32_bf16 v[122:125], v[134:137], v[206:209], v[122:125]
	v_mfma_f32_16x16x32_bf16 v[94:97], v[142:145], v[206:209], v[94:97]
	v_mfma_f32_16x16x32_bf16 v[126:129], v[134:137], v[214:217], v[126:129]
	v_mfma_f32_16x16x32_bf16 v[106:109], v[142:145], v[214:217], v[106:109]
	v_mfma_f32_16x16x32_bf16 v[50:53], v[146:149], v[162:165], v[50:53]
	v_mfma_f32_16x16x32_bf16 v[18:21], v[154:157], v[162:165], v[18:21]
	v_mfma_f32_16x16x32_bf16 v[54:57], v[146:149], v[170:173], v[54:57]
	v_mfma_f32_16x16x32_bf16 v[22:25], v[154:157], v[170:173], v[22:25]
	v_mfma_f32_16x16x32_bf16 v[62:65], v[146:149], v[202:205], v[62:65]
	v_mfma_f32_16x16x32_bf16 v[30:33], v[154:157], v[202:205], v[30:33]
	v_mfma_f32_16x16x32_bf16 v[74:77], v[146:149], v[210:213], v[74:77]
	v_mfma_f32_16x16x32_bf16 v[42:45], v[154:157], v[210:213], v[42:45]
	v_mfma_f32_16x16x32_bf16 v[50:53], v[150:153], v[166:169], v[50:53]
	v_mfma_f32_16x16x32_bf16 v[18:21], v[158:161], v[166:169], v[18:21]
	v_mfma_f32_16x16x32_bf16 v[54:57], v[150:153], v[174:177], v[54:57]
	v_mfma_f32_16x16x32_bf16 v[22:25], v[158:161], v[174:177], v[22:25]
	v_mfma_f32_16x16x32_bf16 v[62:65], v[150:153], v[206:209], v[62:65]
	v_mfma_f32_16x16x32_bf16 v[30:33], v[158:161], v[206:209], v[30:33]
	v_mfma_f32_16x16x32_bf16 v[74:77], v[150:153], v[214:217], v[74:77]
	v_mfma_f32_16x16x32_bf16 v[42:45], v[158:161], v[214:217], v[42:45]
	s_barrier
	s_setprio 0
	s_add_i32 s26, s26, 2
	s_add_u32 s0, s0, 0x100
	s_addc_u32 s1, s1, 0
	s_add_u32 s24, s24, 0x100
	s_addc_u32 s25, s25, 0

.LBB0_787:
	s_ashr_i32 s19, s18, 31
	s_lshl_b64 s[20:21], s[18:19], 21
	s_add_u32 s20, s11, s20
	s_addc_u32 s21, s12, s21
	s_and_b64 s[22:23], s[2:3], exec
	s_cselect_b32 s19, s21, s27
	s_cselect_b32 s50, s20, s26
	s_ashr_i32 s17, s16, 31
	s_lshl_b64 s[22:23], s[16:17], 21
	s_add_u32 s22, s0, s22
	s_addc_u32 s23, s1, s23
	s_and_b64 s[38:39], s[2:3], exec
	s_cselect_b32 s17, s23, s37
	s_cselect_b32 s51, s22, s36
	s_add_u32 s26, s26, 0x100080
	s_addc_u32 s27, s27, 0
	s_add_u32 s52, s36, 0x100
	s_addc_u32 s53, s37, 0
	s_mov_b32 s54, -2
.Lpeelc:
	ds_read_b128 v[156:159], v153
	ds_read_b128 v[160:163], v153 offset:1024
	ds_read_b128 v[164:167], v153 offset:2048
	ds_read_b128 v[168:171], v153 offset:3072
	ds_read_b128 v[172:175], v154
	ds_read_b128 v[176:179], v154 offset:1024
	ds_read_b128 v[180:183], v154 offset:2048
	ds_read_b128 v[184:187], v154 offset:3072
	s_add_u32 s36, s26, 0xfff00080
	s_addc_u32 s37, s27, -1
	s_cmp_eq_u32 s54, 60
	s_cselect_b32 s39, s19, s37
	s_cselect_b32 s38, s50, s36
	s_cselect_b32 s37, s17, s53
	s_cselect_b32 s36, s51, s52
	v_lshl_add_u64 v[148:149], s[26:27], 0, v[140:141]
	s_add_i32 m0, s25, 0xc000
	ds_read_b128 v[188:191], v155
	ds_read_b128 v[192:195], v155 offset:1024
	ds_read_b128 v[196:199], v155 offset:2048
	ds_read_b128 v[200:203], v155 offset:3072
	ds_read_b128 v[204:207], v155 offset:4096
	ds_read_b128 v[208:211], v155 offset:5120
	ds_read_b128 v[212:215], v155 offset:6144
	ds_read_b128 v[216:219], v155 offset:7168
	global_load_lds_dwordx4 v[148:149], off
	v_lshl_add_u64 v[148:149], s[26:27], 0, v[142:143]
	s_add_i32 m0, s25, 0xe000
	s_nop 0
	global_load_lds_dwordx4 v[148:149], off
	s_waitcnt vmcnt(8)
	s_waitcnt lgkmcnt(0)
	s_setprio 1
	s_barrier
	v_mfma_f32_16x16x32_bf16 v[126:129], v[156:159], v[188:191], 0
	v_mfma_f32_16x16x32_bf16 v[122:125], v[164:167], v[188:191], 0
	v_mfma_f32_16x16x32_bf16 v[118:121], v[156:159], v[196:199], 0
	v_mfma_f32_16x16x32_bf16 v[114:117], v[164:167], v[196:199], 0
	v_mfma_f32_16x16x32_bf16 v[94:97], v[156:159], v[204:207], 0
	v_mfma_f32_16x16x32_bf16 v[90:93], v[164:167], v[204:207], 0
	v_mfma_f32_16x16x32_bf16 v[86:89], v[156:159], v[212:215], 0
	v_mfma_f32_16x16x32_bf16 v[82:85], v[164:167], v[212:215], 0
	v_mfma_f32_16x16x32_bf16 v[126:129], v[160:163], v[192:195], v[126:129]
	v_mfma_f32_16x16x32_bf16 v[122:125], v[168:171], v[192:195], v[122:125]
	v_mfma_f32_16x16x32_bf16 v[118:121], v[160:163], v[200:203], v[118:121]
	v_mfma_f32_16x16x32_bf16 v[114:117], v[168:171], v[200:203], v[114:117]
	v_mfma_f32_16x16x32_bf16 v[94:97], v[160:163], v[208:211], v[94:97]
	v_mfma_f32_16x16x32_bf16 v[90:93], v[168:171], v[208:211], v[90:93]
	v_mfma_f32_16x16x32_bf16 v[86:89], v[160:163], v[216:219], v[86:89]
	v_mfma_f32_16x16x32_bf16 v[82:85], v[168:171], v[216:219], v[82:85]
	v_mfma_f32_16x16x32_bf16 v[110:113], v[172:175], v[188:191], 0
	v_mfma_f32_16x16x32_bf16 v[106:109], v[180:183], v[188:191], 0
	v_mfma_f32_16x16x32_bf16 v[102:105], v[172:175], v[196:199], 0
	v_mfma_f32_16x16x32_bf16 v[98:101], v[180:183], v[196:199], 0
	v_mfma_f32_16x16x32_bf16 v[78:81], v[172:175], v[204:207], 0
	v_mfma_f32_16x16x32_bf16 v[74:77], v[180:183], v[204:207], 0
	v_mfma_f32_16x16x32_bf16 v[70:73], v[172:175], v[212:215], 0
	v_mfma_f32_16x16x32_bf16 v[66:69], v[180:183], v[212:215], 0
	v_mfma_f32_16x16x32_bf16 v[110:113], v[176:179], v[192:195], v[110:113]
	v_mfma_f32_16x16x32_bf16 v[106:109], v[184:187], v[192:195], v[106:109]
	v_mfma_f32_16x16x32_bf16 v[102:105], v[176:179], v[200:203], v[102:105]
	v_mfma_f32_16x16x32_bf16 v[98:101], v[184:187], v[200:203], v[98:101]
	v_mfma_f32_16x16x32_bf16 v[78:81], v[176:179], v[208:211], v[78:81]
	v_mfma_f32_16x16x32_bf16 v[74:77], v[184:187], v[208:211], v[74:77]
	v_mfma_f32_16x16x32_bf16 v[70:73], v[176:179], v[216:219], v[70:73]
	v_mfma_f32_16x16x32_bf16 v[66:69], v[184:187], v[216:219], v[66:69]
	s_barrier
	s_setprio 0
	s_add_i32 s55, s44, s13
	v_lshl_add_u64 v[148:149], s[36:37], 0, v[134:135]
	s_mov_b32 m0, s55
	ds_read_b128 v[188:191], v155 offset:16384
	ds_read_b128 v[192:195], v155 offset:17408
	ds_read_b128 v[196:199], v155 offset:18432
	ds_read_b128 v[200:203], v155 offset:19456
	ds_read_b128 v[204:207], v155 offset:20480
	ds_read_b128 v[208:211], v155 offset:21504
	ds_read_b128 v[212:215], v155 offset:22528
	ds_read_b128 v[216:219], v155 offset:23552
	global_load_lds_dwordx4 v[148:149], off
	s_add_i32 m0, s55, 0x2000
	s_add_u32 s56, s36, 0x100000
	v_lshl_add_u64 v[220:221], s[36:37], 0, v[130:131]
	s_addc_u32 s57, s37, 0
	s_add_i32 s55, s45, s13
	global_load_lds_dwordx4 v[220:221], off
	v_lshl_add_u64 v[224:225], s[56:57], 0, v[134:135]
	s_mov_b32 m0, s55
	v_lshl_add_u64 v[226:227], s[38:39], 0, v[132:133]
	global_load_lds_dwordx4 v[224:225], off
	v_lshl_add_u64 v[224:225], s[56:57], 0, v[130:131]
	s_add_i32 m0, s55, 0x2000
	s_nop 0
	global_load_lds_dwordx4 v[224:225], off
	v_lshl_add_u64 v[224:225], s[38:39], 0, v[136:137]
	s_mov_b32 m0, s25
	s_nop 0
	global_load_lds_dwordx4 v[224:225], off
	s_mov_b32 m0, s31
	s_nop 0
	global_load_lds_dwordx4 v[226:227], off
	s_waitcnt vmcnt(8)
	s_waitcnt lgkmcnt(0)
	s_setprio 1
	s_barrier
	v_mfma_f32_16x16x32_bf16 v[62:65], v[156:159], v[188:191], 0
	v_mfma_f32_16x16x32_bf16 v[58:61], v[164:167], v[188:191], 0
	v_mfma_f32_16x16x32_bf16 v[54:57], v[156:159], v[196:199], 0
	v_mfma_f32_16x16x32_bf16 v[50:53], v[164:167], v[196:199], 0
	v_mfma_f32_16x16x32_bf16 v[30:33], v[156:159], v[204:207], 0
	v_mfma_f32_16x16x32_bf16 v[26:29], v[164:167], v[204:207], 0
	v_mfma_f32_16x16x32_bf16 v[22:25], v[156:159], v[212:215], 0
	v_mfma_f32_16x16x32_bf16 v[18:21], v[164:167], v[212:215], 0
	v_mfma_f32_16x16x32_bf16 v[62:65], v[160:163], v[192:195], v[62:65]
	v_mfma_f32_16x16x32_bf16 v[58:61], v[168:171], v[192:195], v[58:61]
	v_mfma_f32_16x16x32_bf16 v[54:57], v[160:163], v[200:203], v[54:57]
	v_mfma_f32_16x16x32_bf16 v[50:53], v[168:171], v[200:203], v[50:53]
	v_mfma_f32_16x16x32_bf16 v[30:33], v[160:163], v[208:211], v[30:33]
	v_mfma_f32_16x16x32_bf16 v[26:29], v[168:171], v[208:211], v[26:29]
	v_mfma_f32_16x16x32_bf16 v[22:25], v[160:163], v[216:219], v[22:25]
	v_mfma_f32_16x16x32_bf16 v[18:21], v[168:171], v[216:219], v[18:21]
	v_mfma_f32_16x16x32_bf16 v[46:49], v[172:175], v[188:191], 0
	v_mfma_f32_16x16x32_bf16 v[42:45], v[180:183], v[188:191], 0
	v_mfma_f32_16x16x32_bf16 v[38:41], v[172:175], v[196:199], 0
	v_mfma_f32_16x16x32_bf16 v[34:37], v[180:183], v[196:199], 0
	v_mfma_f32_16x16x32_bf16 v[14:17], v[172:175], v[204:207], 0
	v_mfma_f32_16x16x32_bf16 v[10:13], v[180:183], v[204:207], 0
	v_mfma_f32_16x16x32_bf16 v[6:9], v[172:175], v[212:215], 0
	v_mfma_f32_16x16x32_bf16 v[2:5], v[180:183], v[212:215], 0
	v_mfma_f32_16x16x32_bf16 v[46:49], v[176:179], v[192:195], v[46:49]
	v_mfma_f32_16x16x32_bf16 v[42:45], v[184:187], v[192:195], v[42:45]
	v_mfma_f32_16x16x32_bf16 v[38:41], v[176:179], v[200:203], v[38:41]
	v_mfma_f32_16x16x32_bf16 v[34:37], v[184:187], v[200:203], v[34:37]
	v_mfma_f32_16x16x32_bf16 v[14:17], v[176:179], v[208:211], v[14:17]
	v_mfma_f32_16x16x32_bf16 v[10:13], v[184:187], v[208:211], v[10:13]
	v_mfma_f32_16x16x32_bf16 v[6:9], v[176:179], v[216:219], v[6:9]
	v_mfma_f32_16x16x32_bf16 v[2:5], v[184:187], v[216:219], v[2:5]
	s_barrier
	s_setprio 0
	s_add_i32 s55, 0, 0x18000
	s_add_i32 s56, 0, 0x1c000
	v_add_u32_e32 v168, s55, v151
	v_add_u32_e32 v184, s56, v151
	ds_read_b128 v[156:159], v168
	ds_read_b128 v[160:163], v168 offset:1024
	ds_read_b128 v[164:167], v168 offset:2048
	ds_read_b128 v[168:171], v168 offset:3072
	ds_read_b128 v[172:175], v184
	ds_read_b128 v[176:179], v184 offset:1024
	ds_read_b128 v[180:183], v184 offset:2048
	ds_read_b128 v[184:187], v184 offset:3072
	s_add_u32 s38, s38, 0x100000
	s_addc_u32 s39, s39, 0
	s_mov_b32 m0, s34
	v_lshl_add_u64 v[228:229], s[38:39], 0, v[136:137]
	ds_read_b128 v[188:191], v155 offset:32768
	ds_read_b128 v[192:195], v155 offset:33792
	ds_read_b128 v[196:199], v155 offset:34816
	ds_read_b128 v[200:203], v155 offset:35840
	ds_read_b128 v[204:207], v155 offset:36864
	ds_read_b128 v[208:211], v155 offset:37888
	ds_read_b128 v[212:215], v155 offset:38912
	ds_read_b128 v[216:219], v155 offset:39936
	global_load_lds_dwordx4 v[228:229], off
	v_lshl_add_u64 v[228:229], s[38:39], 0, v[132:133]
	s_mov_b32 m0, s35
	s_nop 0
	global_load_lds_dwordx4 v[228:229], off
	s_waitcnt vmcnt(8)
	s_waitcnt lgkmcnt(0)
	s_setprio 1
	s_barrier
	v_mfma_f32_16x16x32_bf16 v[126:129], v[156:159], v[188:191], v[126:129]
	v_mfma_f32_16x16x32_bf16 v[122:125], v[164:167], v[188:191], v[122:125]
	v_mfma_f32_16x16x32_bf16 v[118:121], v[156:159], v[196:199], v[118:121]
	v_mfma_f32_16x16x32_bf16 v[114:117], v[164:167], v[196:199], v[114:117]
	v_mfma_f32_16x16x32_bf16 v[94:97], v[156:159], v[204:207], v[94:97]
	v_mfma_f32_16x16x32_bf16 v[90:93], v[164:167], v[204:207], v[90:93]
	v_mfma_f32_16x16x32_bf16 v[86:89], v[156:159], v[212:215], v[86:89]
	v_mfma_f32_16x16x32_bf16 v[82:85], v[164:167], v[212:215], v[82:85]
	v_mfma_f32_16x16x32_bf16 v[126:129], v[160:163], v[192:195], v[126:129]
	v_mfma_f32_16x16x32_bf16 v[122:125], v[168:171], v[192:195], v[122:125]
	v_mfma_f32_16x16x32_bf16 v[118:121], v[160:163], v[200:203], v[118:121]
	v_mfma_f32_16x16x32_bf16 v[114:117], v[168:171], v[200:203], v[114:117]
	v_mfma_f32_16x16x32_bf16 v[94:97], v[160:163], v[208:211], v[94:97]
	v_mfma_f32_16x16x32_bf16 v[90:93], v[168:171], v[208:211], v[90:93]
	v_mfma_f32_16x16x32_bf16 v[86:89], v[160:163], v[216:219], v[86:89]
	v_mfma_f32_16x16x32_bf16 v[82:85], v[168:171], v[216:219], v[82:85]
	v_mfma_f32_16x16x32_bf16 v[110:113], v[172:175], v[188:191], v[110:113]
	v_mfma_f32_16x16x32_bf16 v[106:109], v[180:183], v[188:191], v[106:109]
	v_mfma_f32_16x16x32_bf16 v[102:105], v[172:175], v[196:199], v[102:105]
	v_mfma_f32_16x16x32_bf16 v[98:101], v[180:183], v[196:199], v[98:101]
	v_mfma_f32_16x16x32_bf16 v[78:81], v[172:175], v[204:207], v[78:81]
	v_mfma_f32_16x16x32_bf16 v[74:77], v[180:183], v[204:207], v[74:77]
	v_mfma_f32_16x16x32_bf16 v[70:73], v[172:175], v[212:215], v[70:73]
	v_mfma_f32_16x16x32_bf16 v[66:69], v[180:183], v[212:215], v[66:69]
	v_mfma_f32_16x16x32_bf16 v[110:113], v[176:179], v[192:195], v[110:113]
	v_mfma_f32_16x16x32_bf16 v[106:109], v[184:187], v[192:195], v[106:109]
	v_mfma_f32_16x16x32_bf16 v[102:105], v[176:179], v[200:203], v[102:105]
	v_mfma_f32_16x16x32_bf16 v[98:101], v[184:187], v[200:203], v[98:101]
	v_mfma_f32_16x16x32_bf16 v[78:81], v[176:179], v[208:211], v[78:81]
	v_mfma_f32_16x16x32_bf16 v[74:77], v[184:187], v[208:211], v[74:77]
	v_mfma_f32_16x16x32_bf16 v[70:73], v[176:179], v[216:219], v[70:73]
	v_mfma_f32_16x16x32_bf16 v[66:69], v[184:187], v[216:219], v[66:69]
	s_barrier
	s_setprio 0
	s_add_i32 s38, s55, s13
	v_lshl_add_u64 v[148:149], v[148:149], 0, s[6:7]
	s_mov_b32 m0, s38
	ds_read_b128 v[188:191], v155 offset:49152
	ds_read_b128 v[192:195], v155 offset:50176
	ds_read_b128 v[196:199], v155 offset:51200
	ds_read_b128 v[200:203], v155 offset:52224
	ds_read_b128 v[204:207], v155 offset:53248
	ds_read_b128 v[208:211], v155 offset:54272
	ds_read_b128 v[212:215], v155 offset:55296
	ds_read_b128 v[216:219], v155 offset:56320
	global_load_lds_dwordx4 v[148:149], off
	s_add_i32 m0, s38, 0x2000
	s_add_u32 s36, s36, 0x100080
	v_lshl_add_u64 v[148:149], v[220:221], 0, s[6:7]
	s_addc_u32 s37, s37, 0
	s_add_i32 s38, s56, s13
	global_load_lds_dwordx4 v[148:149], off
	v_lshl_add_u64 v[148:149], s[36:37], 0, v[134:135]
	s_mov_b32 m0, s38
	s_nop 0
	global_load_lds_dwordx4 v[148:149], off
	v_lshl_add_u64 v[148:149], s[36:37], 0, v[130:131]
	s_add_i32 m0, s38, 0x2000
	s_nop 0
	global_load_lds_dwordx4 v[148:149], off
	v_lshl_add_u64 v[148:149], v[224:225], 0, s[6:7]
	s_mov_b32 m0, s41
	s_nop 0
	global_load_lds_dwordx4 v[148:149], off
	v_lshl_add_u64 v[148:149], v[226:227], 0, s[6:7]
	s_mov_b32 m0, s42
	s_nop 0
	global_load_lds_dwordx4 v[148:149], off
	s_waitcnt vmcnt(8)
	s_waitcnt lgkmcnt(0)
	s_setprio 1
	s_barrier
	v_mfma_f32_16x16x32_bf16 v[62:65], v[156:159], v[188:191], v[62:65]
	v_mfma_f32_16x16x32_bf16 v[58:61], v[164:167], v[188:191], v[58:61]
	v_mfma_f32_16x16x32_bf16 v[54:57], v[156:159], v[196:199], v[54:57]
	v_mfma_f32_16x16x32_bf16 v[50:53], v[164:167], v[196:199], v[50:53]
	v_mfma_f32_16x16x32_bf16 v[30:33], v[156:159], v[204:207], v[30:33]
	v_mfma_f32_16x16x32_bf16 v[26:29], v[164:167], v[204:207], v[26:29]
	v_mfma_f32_16x16x32_bf16 v[22:25], v[156:159], v[212:215], v[22:25]
	v_mfma_f32_16x16x32_bf16 v[18:21], v[164:167], v[212:215], v[18:21]
	v_mfma_f32_16x16x32_bf16 v[62:65], v[160:163], v[192:195], v[62:65]
	v_mfma_f32_16x16x32_bf16 v[58:61], v[168:171], v[192:195], v[58:61]
	v_mfma_f32_16x16x32_bf16 v[54:57], v[160:163], v[200:203], v[54:57]
	v_mfma_f32_16x16x32_bf16 v[50:53], v[168:171], v[200:203], v[50:53]
	v_mfma_f32_16x16x32_bf16 v[30:33], v[160:163], v[208:211], v[30:33]
	v_mfma_f32_16x16x32_bf16 v[26:29], v[168:171], v[208:211], v[26:29]
	v_mfma_f32_16x16x32_bf16 v[22:25], v[160:163], v[216:219], v[22:25]
	v_mfma_f32_16x16x32_bf16 v[18:21], v[168:171], v[216:219], v[18:21]
	v_mfma_f32_16x16x32_bf16 v[46:49], v[172:175], v[188:191], v[46:49]
	v_mfma_f32_16x16x32_bf16 v[42:45], v[180:183], v[188:191], v[42:45]
	v_mfma_f32_16x16x32_bf16 v[38:41], v[172:175], v[196:199], v[38:41]
	v_mfma_f32_16x16x32_bf16 v[34:37], v[180:183], v[196:199], v[34:37]
	v_mfma_f32_16x16x32_bf16 v[14:17], v[172:175], v[204:207], v[14:17]
	v_mfma_f32_16x16x32_bf16 v[10:13], v[180:183], v[204:207], v[10:13]
	v_mfma_f32_16x16x32_bf16 v[6:9], v[172:175], v[212:215], v[6:9]
	v_mfma_f32_16x16x32_bf16 v[2:5], v[180:183], v[212:215], v[2:5]
	v_mfma_f32_16x16x32_bf16 v[46:49], v[176:179], v[192:195], v[46:49]
	v_mfma_f32_16x16x32_bf16 v[42:45], v[184:187], v[192:195], v[42:45]
	v_mfma_f32_16x16x32_bf16 v[38:41], v[176:179], v[200:203], v[38:41]
	v_mfma_f32_16x16x32_bf16 v[34:37], v[184:187], v[200:203], v[34:37]
	v_mfma_f32_16x16x32_bf16 v[14:17], v[176:179], v[208:211], v[14:17]
	v_mfma_f32_16x16x32_bf16 v[10:13], v[184:187], v[208:211], v[10:13]
	v_mfma_f32_16x16x32_bf16 v[6:9], v[176:179], v[216:219], v[6:9]
	v_mfma_f32_16x16x32_bf16 v[2:5], v[184:187], v[216:219], v[2:5]
	s_barrier
	s_setprio 0
	s_add_i32 s54, s54, 2
	s_add_u32 s26, s26, 0x100
	s_addc_u32 s27, s27, 0
	s_add_u32 s52, s52, 0x100
	s_addc_u32 s53, s53, 0

.Lpeeld:
	ds_read_b128 v[130:133], v207
	ds_read_b128 v[134:137], v207 offset:1024
	ds_read_b128 v[138:141], v207 offset:2048
	ds_read_b128 v[142:145], v207 offset:3072
	ds_read_b128 v[146:149], v208
	ds_read_b128 v[172:175], v208 offset:1024
	ds_read_b128 v[176:179], v208 offset:2048
	ds_read_b128 v[210:213], v208 offset:3072
	s_add_u32 s10, s8, 0xffd50080
	s_addc_u32 s11, s9, -1
	s_cmpk_eq_i32 s16, 0xa8
	s_cselect_b32 s13, s25, s11
	s_cselect_b32 s12, s24, s10
	s_cselect_b32 s11, s41, s15
	s_cselect_b32 s10, s40, s14
	v_lshl_add_u64 v[180:181], s[8:9], 0, v[166:167]
	s_add_i32 m0, s48, 0xc000
	ds_read_b128 v[214:217], v202
	ds_read_b128 v[218:221], v202 offset:1024
	ds_read_b128 v[224:227], v202 offset:2048
	ds_read_b128 v[228:231], v202 offset:3072
	ds_read_b128 v[232:235], v202 offset:4096
	ds_read_b128 v[236:239], v202 offset:5120
	ds_read_b128 v[240:243], v202 offset:6144
	ds_read_b128 v[244:247], v202 offset:7168
	global_load_lds_dwordx4 v[180:181], off
	v_lshl_add_u64 v[180:181], s[8:9], 0, v[168:169]
	s_add_i32 m0, s48, 0xe000
	s_nop 0
	global_load_lds_dwordx4 v[180:181], off
	s_waitcnt vmcnt(8)
	s_waitcnt lgkmcnt(0)
	s_setprio 1
	s_barrier
	v_mfma_f32_16x16x32_bf16 v[90:93], v[130:133], v[214:217], 0
	v_mfma_f32_16x16x32_bf16 v[74:77], v[138:141], v[214:217], 0
	v_mfma_f32_16x16x32_bf16 v[46:49], v[130:133], v[224:227], 0
	v_mfma_f32_16x16x32_bf16 v[42:45], v[138:141], v[224:227], 0
	v_mfma_f32_16x16x32_bf16 v[126:129], v[130:133], v[232:235], 0
	v_mfma_f32_16x16x32_bf16 v[122:125], v[138:141], v[232:235], 0
	v_mfma_f32_16x16x32_bf16 v[110:113], v[130:133], v[240:243], 0
	v_mfma_f32_16x16x32_bf16 v[106:109], v[138:141], v[240:243], 0
	v_mfma_f32_16x16x32_bf16 v[90:93], v[134:137], v[218:221], v[90:93]
	v_mfma_f32_16x16x32_bf16 v[74:77], v[142:145], v[218:221], v[74:77]
	v_mfma_f32_16x16x32_bf16 v[46:49], v[134:137], v[228:231], v[46:49]
	v_mfma_f32_16x16x32_bf16 v[42:45], v[142:145], v[228:231], v[42:45]
	v_mfma_f32_16x16x32_bf16 v[126:129], v[134:137], v[236:239], v[126:129]
	v_mfma_f32_16x16x32_bf16 v[122:125], v[142:145], v[236:239], v[122:125]
	v_mfma_f32_16x16x32_bf16 v[110:113], v[134:137], v[244:247], v[110:113]
	v_mfma_f32_16x16x32_bf16 v[106:109], v[142:145], v[244:247], v[106:109]
	v_mfma_f32_16x16x32_bf16 v[70:73], v[146:149], v[214:217], 0
	v_mfma_f32_16x16x32_bf16 v[66:69], v[176:179], v[214:217], 0
	v_mfma_f32_16x16x32_bf16 v[34:37], v[146:149], v[224:227], 0
	v_mfma_f32_16x16x32_bf16 v[38:41], v[176:179], v[224:227], 0
	v_mfma_f32_16x16x32_bf16 v[118:121], v[146:149], v[232:235], 0
	v_mfma_f32_16x16x32_bf16 v[114:117], v[176:179], v[232:235], 0
	v_mfma_f32_16x16x32_bf16 v[102:105], v[146:149], v[240:243], 0
	v_mfma_f32_16x16x32_bf16 v[98:101], v[176:179], v[240:243], 0
	v_mfma_f32_16x16x32_bf16 v[70:73], v[172:175], v[218:221], v[70:73]
	v_mfma_f32_16x16x32_bf16 v[66:69], v[210:213], v[218:221], v[66:69]
	v_mfma_f32_16x16x32_bf16 v[34:37], v[172:175], v[228:231], v[34:37]
	v_mfma_f32_16x16x32_bf16 v[38:41], v[210:213], v[228:231], v[38:41]
	v_mfma_f32_16x16x32_bf16 v[118:121], v[172:175], v[236:239], v[118:121]
	v_mfma_f32_16x16x32_bf16 v[114:117], v[210:213], v[236:239], v[114:117]
	v_mfma_f32_16x16x32_bf16 v[102:105], v[172:175], v[244:247], v[102:105]
	v_mfma_f32_16x16x32_bf16 v[98:101], v[210:213], v[244:247], v[98:101]
	s_barrier
	s_setprio 0
	s_add_i32 s17, s57, s46
	v_lshl_add_u64 v[180:181], s[10:11], 0, v[150:151]
	s_mov_b32 m0, s17
	ds_read_b128 v[214:217], v202 offset:16384
	ds_read_b128 v[218:221], v202 offset:17408
	ds_read_b128 v[224:227], v202 offset:18432
	ds_read_b128 v[228:231], v202 offset:19456
	ds_read_b128 v[232:235], v202 offset:20480
	ds_read_b128 v[236:239], v202 offset:21504
	ds_read_b128 v[240:243], v202 offset:22528
	ds_read_b128 v[244:247], v202 offset:23552
	global_load_lds_dwordx4 v[180:181], off
	s_add_i32 m0, s17, 0x2000
	s_add_u32 s18, s10, 0x2b0000
	v_lshl_add_u64 v[248:249], s[10:11], 0, v[152:153]
	s_addc_u32 s19, s11, 0
	s_add_i32 s17, s58, s46
	global_load_lds_dwordx4 v[248:249], off
	v_lshl_add_u64 v[250:251], s[18:19], 0, v[150:151]
	s_mov_b32 m0, s17
	v_lshl_add_u64 v[252:253], s[12:13], 0, v[152:153]
	global_load_lds_dwordx4 v[250:251], off
	v_lshl_add_u64 v[250:251], s[18:19], 0, v[152:153]
	s_add_i32 m0, s17, 0x2000
	s_nop 0
	global_load_lds_dwordx4 v[250:251], off
	v_lshl_add_u64 v[250:251], s[12:13], 0, v[150:151]
	s_mov_b32 m0, s48
	s_nop 0
	global_load_lds_dwordx4 v[250:251], off
	s_mov_b32 m0, s49
	s_nop 0
	global_load_lds_dwordx4 v[252:253], off
	s_waitcnt vmcnt(8)
	s_waitcnt lgkmcnt(0)
	s_setprio 1
	s_barrier
	v_mfma_f32_16x16x32_bf16 v[94:97], v[130:133], v[214:217], 0
	v_mfma_f32_16x16x32_bf16 v[86:89], v[138:141], v[214:217], 0
	v_mfma_f32_16x16x32_bf16 v[82:85], v[130:133], v[224:227], 0
	v_mfma_f32_16x16x32_bf16 v[78:81], v[138:141], v[224:227], 0
	v_mfma_f32_16x16x32_bf16 v[30:33], v[130:133], v[232:235], 0
	v_mfma_f32_16x16x32_bf16 v[26:29], v[138:141], v[232:235], 0
	v_mfma_f32_16x16x32_bf16 v[22:25], v[130:133], v[240:243], 0
	v_mfma_f32_16x16x32_bf16 v[18:21], v[138:141], v[240:243], 0
	v_mfma_f32_16x16x32_bf16 v[94:97], v[134:137], v[218:221], v[94:97]
	v_mfma_f32_16x16x32_bf16 v[86:89], v[142:145], v[218:221], v[86:89]
	v_mfma_f32_16x16x32_bf16 v[82:85], v[134:137], v[228:231], v[82:85]
	v_mfma_f32_16x16x32_bf16 v[78:81], v[142:145], v[228:231], v[78:81]
	v_mfma_f32_16x16x32_bf16 v[30:33], v[134:137], v[236:239], v[30:33]
	v_mfma_f32_16x16x32_bf16 v[26:29], v[142:145], v[236:239], v[26:29]
	v_mfma_f32_16x16x32_bf16 v[22:25], v[134:137], v[244:247], v[22:25]
	v_mfma_f32_16x16x32_bf16 v[18:21], v[142:145], v[244:247], v[18:21]
	v_mfma_f32_16x16x32_bf16 v[62:65], v[146:149], v[214:217], 0
	v_mfma_f32_16x16x32_bf16 v[58:61], v[176:179], v[214:217], 0
	v_mfma_f32_16x16x32_bf16 v[54:57], v[146:149], v[224:227], 0
	v_mfma_f32_16x16x32_bf16 v[50:53], v[176:179], v[224:227], 0
	v_mfma_f32_16x16x32_bf16 v[14:17], v[146:149], v[232:235], 0
	v_mfma_f32_16x16x32_bf16 v[6:9], v[176:179], v[232:235], 0
	v_mfma_f32_16x16x32_bf16 v[10:13], v[146:149], v[240:243], 0
	v_mfma_f32_16x16x32_bf16 v[2:5], v[176:179], v[240:243], 0
	v_mfma_f32_16x16x32_bf16 v[62:65], v[172:175], v[218:221], v[62:65]
	v_mfma_f32_16x16x32_bf16 v[58:61], v[210:213], v[218:221], v[58:61]
	v_mfma_f32_16x16x32_bf16 v[54:57], v[172:175], v[228:231], v[54:57]
	v_mfma_f32_16x16x32_bf16 v[50:53], v[210:213], v[228:231], v[50:53]
	v_mfma_f32_16x16x32_bf16 v[14:17], v[172:175], v[236:239], v[14:17]
	v_mfma_f32_16x16x32_bf16 v[6:9], v[210:213], v[236:239], v[6:9]
	v_mfma_f32_16x16x32_bf16 v[10:13], v[172:175], v[244:247], v[10:13]
	v_mfma_f32_16x16x32_bf16 v[2:5], v[210:213], v[244:247], v[2:5]
	s_barrier
	s_setprio 0
	s_add_i32 s17, 0, 0x18000
	s_add_i32 s18, 0, 0x1c000
	v_add_u32_e32 v142, s17, v182
	v_add_u32_e32 v154, s18, v182
	ds_read_b128 v[130:133], v142
	ds_read_b128 v[134:137], v142 offset:1024
	ds_read_b128 v[138:141], v142 offset:2048
	ds_read_b128 v[142:145], v142 offset:3072
	ds_read_b128 v[146:149], v154
	ds_read_b128 v[172:175], v154 offset:1024
	ds_read_b128 v[176:179], v154 offset:2048
	ds_read_b128 v[210:213], v154 offset:3072
	s_add_u32 s12, s12, 0x2b0000
	s_addc_u32 s13, s13, 0
	s_mov_b32 m0, s50
	v_lshl_add_u64 v[188:189], s[12:13], 0, v[150:151]
	ds_read_b128 v[214:217], v202 offset:32768
	ds_read_b128 v[218:221], v202 offset:33792
	ds_read_b128 v[224:227], v202 offset:34816
	ds_read_b128 v[228:231], v202 offset:35840
	ds_read_b128 v[232:235], v202 offset:36864
	ds_read_b128 v[236:239], v202 offset:37888
	ds_read_b128 v[240:243], v202 offset:38912
	ds_read_b128 v[244:247], v202 offset:39936
	global_load_lds_dwordx4 v[188:189], off
	v_lshl_add_u64 v[188:189], s[12:13], 0, v[152:153]
	s_mov_b32 m0, s51
	s_nop 0
	global_load_lds_dwordx4 v[188:189], off
	s_waitcnt vmcnt(8)
	s_waitcnt lgkmcnt(0)
	s_setprio 1
	s_barrier
	v_mfma_f32_16x16x32_bf16 v[90:93], v[130:133], v[214:217], v[90:93]
	v_mfma_f32_16x16x32_bf16 v[74:77], v[138:141], v[214:217], v[74:77]
	v_mfma_f32_16x16x32_bf16 v[46:49], v[130:133], v[224:227], v[46:49]
	v_mfma_f32_16x16x32_bf16 v[42:45], v[138:141], v[224:227], v[42:45]
	v_mfma_f32_16x16x32_bf16 v[126:129], v[130:133], v[232:235], v[126:129]
	v_mfma_f32_16x16x32_bf16 v[122:125], v[138:141], v[232:235], v[122:125]
	v_mfma_f32_16x16x32_bf16 v[110:113], v[130:133], v[240:243], v[110:113]
	v_mfma_f32_16x16x32_bf16 v[106:109], v[138:141], v[240:243], v[106:109]
	v_mfma_f32_16x16x32_bf16 v[90:93], v[134:137], v[218:221], v[90:93]
	v_mfma_f32_16x16x32_bf16 v[74:77], v[142:145], v[218:221], v[74:77]
	v_mfma_f32_16x16x32_bf16 v[46:49], v[134:137], v[228:231], v[46:49]
	v_mfma_f32_16x16x32_bf16 v[42:45], v[142:145], v[228:231], v[42:45]
	v_mfma_f32_16x16x32_bf16 v[126:129], v[134:137], v[236:239], v[126:129]
	v_mfma_f32_16x16x32_bf16 v[122:125], v[142:145], v[236:239], v[122:125]
	v_mfma_f32_16x16x32_bf16 v[110:113], v[134:137], v[244:247], v[110:113]
	v_mfma_f32_16x16x32_bf16 v[106:109], v[142:145], v[244:247], v[106:109]
	v_mfma_f32_16x16x32_bf16 v[70:73], v[146:149], v[214:217], v[70:73]
	v_mfma_f32_16x16x32_bf16 v[66:69], v[176:179], v[214:217], v[66:69]
	v_mfma_f32_16x16x32_bf16 v[34:37], v[146:149], v[224:227], v[34:37]
	v_mfma_f32_16x16x32_bf16 v[38:41], v[176:179], v[224:227], v[38:41]
	v_mfma_f32_16x16x32_bf16 v[118:121], v[146:149], v[232:235], v[118:121]
	v_mfma_f32_16x16x32_bf16 v[114:117], v[176:179], v[232:235], v[114:117]
	v_mfma_f32_16x16x32_bf16 v[102:105], v[146:149], v[240:243], v[102:105]
	v_mfma_f32_16x16x32_bf16 v[98:101], v[176:179], v[240:243], v[98:101]
	v_mfma_f32_16x16x32_bf16 v[70:73], v[172:175], v[218:221], v[70:73]
	v_mfma_f32_16x16x32_bf16 v[66:69], v[210:213], v[218:221], v[66:69]
	v_mfma_f32_16x16x32_bf16 v[34:37], v[172:175], v[228:231], v[34:37]
	v_mfma_f32_16x16x32_bf16 v[38:41], v[210:213], v[228:231], v[38:41]
	v_mfma_f32_16x16x32_bf16 v[118:121], v[172:175], v[236:239], v[118:121]
	v_mfma_f32_16x16x32_bf16 v[114:117], v[210:213], v[236:239], v[114:117]
	v_mfma_f32_16x16x32_bf16 v[102:105], v[172:175], v[244:247], v[102:105]
	v_mfma_f32_16x16x32_bf16 v[98:101], v[210:213], v[244:247], v[98:101]
	s_barrier
	s_setprio 0
	s_add_i32 s12, s17, s46
	v_lshl_add_u64 v[180:181], v[180:181], 0, s[30:31]
	s_mov_b32 m0, s12
	ds_read_b128 v[214:217], v202 offset:49152
	ds_read_b128 v[218:221], v202 offset:50176
	ds_read_b128 v[224:227], v202 offset:51200
	ds_read_b128 v[228:231], v202 offset:52224
	ds_read_b128 v[232:235], v202 offset:53248
	ds_read_b128 v[236:239], v202 offset:54272
	ds_read_b128 v[240:243], v202 offset:55296
	ds_read_b128 v[244:247], v202 offset:56320
	global_load_lds_dwordx4 v[180:181], off
	s_add_i32 m0, s12, 0x2000
	s_add_u32 s10, s10, 0x2b0080
	v_lshl_add_u64 v[180:181], v[248:249], 0, s[30:31]
	s_addc_u32 s11, s11, 0
	s_add_i32 s12, s18, s46
	global_load_lds_dwordx4 v[180:181], off
	v_lshl_add_u64 v[180:181], s[10:11], 0, v[150:151]
	s_mov_b32 m0, s12
	s_nop 0
	global_load_lds_dwordx4 v[180:181], off
	v_lshl_add_u64 v[180:181], s[10:11], 0, v[152:153]
	s_add_i32 m0, s12, 0x2000
	s_nop 0
	global_load_lds_dwordx4 v[180:181], off
	v_lshl_add_u64 v[180:181], v[250:251], 0, s[30:31]
	s_mov_b32 m0, s52
	s_nop 0
	global_load_lds_dwordx4 v[180:181], off
	v_lshl_add_u64 v[180:181], v[252:253], 0, s[30:31]
	s_mov_b32 m0, s53
	s_nop 0
	global_load_lds_dwordx4 v[180:181], off
	s_waitcnt vmcnt(8)
	s_waitcnt lgkmcnt(0)
	s_setprio 1
	s_barrier
	v_mfma_f32_16x16x32_bf16 v[94:97], v[130:133], v[214:217], v[94:97]
	v_mfma_f32_16x16x32_bf16 v[86:89], v[138:141], v[214:217], v[86:89]
	v_mfma_f32_16x16x32_bf16 v[82:85], v[130:133], v[224:227], v[82:85]
	v_mfma_f32_16x16x32_bf16 v[78:81], v[138:141], v[224:227], v[78:81]
	v_mfma_f32_16x16x32_bf16 v[30:33], v[130:133], v[232:235], v[30:33]
	v_mfma_f32_16x16x32_bf16 v[26:29], v[138:141], v[232:235], v[26:29]
	v_mfma_f32_16x16x32_bf16 v[22:25], v[130:133], v[240:243], v[22:25]
	v_mfma_f32_16x16x32_bf16 v[18:21], v[138:141], v[240:243], v[18:21]
	v_mfma_f32_16x16x32_bf16 v[94:97], v[134:137], v[218:221], v[94:97]
	v_mfma_f32_16x16x32_bf16 v[86:89], v[142:145], v[218:221], v[86:89]
	v_mfma_f32_16x16x32_bf16 v[82:85], v[134:137], v[228:231], v[82:85]
	v_mfma_f32_16x16x32_bf16 v[78:81], v[142:145], v[228:231], v[78:81]
	v_mfma_f32_16x16x32_bf16 v[30:33], v[134:137], v[236:239], v[30:33]
	v_mfma_f32_16x16x32_bf16 v[26:29], v[142:145], v[236:239], v[26:29]
	v_mfma_f32_16x16x32_bf16 v[22:25], v[134:137], v[244:247], v[22:25]
	v_mfma_f32_16x16x32_bf16 v[18:21], v[142:145], v[244:247], v[18:21]
	v_mfma_f32_16x16x32_bf16 v[62:65], v[146:149], v[214:217], v[62:65]
	v_mfma_f32_16x16x32_bf16 v[58:61], v[176:179], v[214:217], v[58:61]
	v_mfma_f32_16x16x32_bf16 v[54:57], v[146:149], v[224:227], v[54:57]
	v_mfma_f32_16x16x32_bf16 v[50:53], v[176:179], v[224:227], v[50:53]
	v_mfma_f32_16x16x32_bf16 v[14:17], v[146:149], v[232:235], v[14:17]
	v_mfma_f32_16x16x32_bf16 v[6:9], v[176:179], v[232:235], v[6:9]
	v_mfma_f32_16x16x32_bf16 v[10:13], v[146:149], v[240:243], v[10:13]
	v_mfma_f32_16x16x32_bf16 v[2:5], v[176:179], v[240:243], v[2:5]
	v_mfma_f32_16x16x32_bf16 v[62:65], v[172:175], v[218:221], v[62:65]
	v_mfma_f32_16x16x32_bf16 v[58:61], v[210:213], v[218:221], v[58:61]
	v_mfma_f32_16x16x32_bf16 v[54:57], v[172:175], v[228:231], v[54:57]
	v_mfma_f32_16x16x32_bf16 v[50:53], v[210:213], v[228:231], v[50:53]
	v_mfma_f32_16x16x32_bf16 v[14:17], v[172:175], v[236:239], v[14:17]
	v_mfma_f32_16x16x32_bf16 v[6:9], v[210:213], v[236:239], v[6:9]
	v_mfma_f32_16x16x32_bf16 v[10:13], v[172:175], v[244:247], v[10:13]
	v_mfma_f32_16x16x32_bf16 v[2:5], v[210:213], v[244:247], v[2:5]
	s_barrier
	s_setprio 0
	s_add_i32 s16, s16, 2
	s_add_u32 s8, s8, 0x100
	s_addc_u32 s9, s9, 0
	s_add_u32 s14, s14, 0x100
	s_addc_u32 s15, s15, 0
